# plus attention loop: 12 redundant VALU per tile pair removed (0 + x sum starts, canonicalising max(x,x))
# speedup vs baseline: 1.0035x; 1.0035x over previous
.LBB0_961:
	s_waitcnt vmcnt(5)
	s_barrier
	s_mov_b32 s19, s5
	s_mov_b32 s5, s25
	s_mul_i32 s9, s25, 0x6000
	s_add_i32 s25, s9, 0
	v_add_u32_e32 v124, s25, v225
	ds_read_b128 v[120:123], v124
	ds_read_b128 v[160:163], v124 offset:4096
	ds_read_b128 v[168:171], v124 offset:8192
	ds_read_b128 v[172:175], v124 offset:12288
	s_waitcnt lgkmcnt(0)
	v_mfma_f32_16x16x32_bf16 v[124:127], v[120:123], v[4:7], v[48:51]
	v_exp_f32_e32 v188, v148
	v_exp_f32_e32 v189, v149
	v_mfma_f32_16x16x32_bf16 v[120:123], v[120:123], v[40:43], v[52:55]
	v_add_u32_e32 v196, s25, v234
	ds_read_b128 v[184:187], v196
	v_exp_f32_e32 v194, v150
	v_exp_f32_e32 v195, v151
	v_mfma_f32_16x16x32_bf16 v[148:151], v[160:163], v[4:7], v[48:51]
	v_add_f32_e32 v180, v157, v156
	v_add_f32_e32 v181, v145, v144
	v_mfma_f32_16x16x32_bf16 v[160:163], v[160:163], v[40:43], v[52:55]
	ds_read_b128 v[176:179], v196 offset:4096
	v_mfma_f32_16x16x32_bf16 v[164:167], v[168:171], v[4:7], v[48:51]
	v_exp_f32_e32 v190, v140
	v_exp_f32_e32 v191, v141
	v_add_f32_e32 v206, v158, v180
	v_mfma_f32_16x16x32_bf16 v[168:171], v[168:171], v[40:43], v[52:55]
	v_add_f32_e32 v207, v146, v181
	ds_read_b128 v[180:183], v196 offset:8192
	v_exp_f32_e32 v192, v142
	v_exp_f32_e32 v193, v143
	v_mfma_f32_16x16x32_bf16 v[140:143], v[172:175], v[4:7], v[48:51]
	v_add_f32_e32 v206, v159, v206
	v_add_f32_e32 v207, v147, v207
	v_mfma_f32_16x16x32_bf16 v[172:175], v[172:175], v[40:43], v[52:55]
	s_add_i32 s9, s4, -1
	s_cmp_ge_u32 s9, s2
	s_cbranch_scc1 .LBB0_963
	s_add_u32 s9, s6, s30
	s_addc_u32 s35, s7, s31
	s_add_u32 s34, s9, 0x180000
	s_addc_u32 s35, s35, 0
	s_add_u32 s36, s10, 0xffffe000
	s_mul_i32 s9, s8, 0x6000
	s_addc_u32 s37, s11, -1
	s_add_i32 s9, s9, 0
	s_add_i32 s48, s9, s77
	s_mov_b32 m0, s48
	s_add_i32 s9, s9, s97
	global_load_lds_dwordx4 v227, s[34:35]
	s_add_i32 m0, s48, 0x400
	s_nop 0
	global_load_lds_dwordx4 v229, s[34:35]
	s_add_i32 m0, s9, 0x4000
	s_nop 0
	global_load_lds_dwordx4 v232, s[36:37]
.LBB0_963:
	s_add_u32 s36, s28, s30
	s_addc_u32 s37, s29, s31
	s_add_u32 s34, s36, 0x100000
	s_addc_u32 s35, s37, 0
	s_lshl_b32 s9, s19, 14
	s_add_i32 s48, s95, s9
	s_mov_b32 m0, s48
	s_nop 0
	global_load_lds_dwordx4 v228, s[34:35]
	s_add_i32 m0, s48, 0x400
	s_nop 0
	global_load_lds_dwordx4 v231, s[34:35]
	ds_read_b128 v[236:239], v196 offset:12288
	s_waitcnt lgkmcnt(0)
	v_mfma_f32_16x16x32_bf16 v[120:123], v[184:187], v[36:39], v[120:123]
	v_exp_f32_e32 v196, v132
	v_exp_f32_e32 v208, v133
	v_add_f32_e32 v206, v152, v206
	v_add_f32_e32 v207, v136, v207
	v_mfma_f32_16x16x32_bf16 v[124:127], v[184:187], v[0:3], v[124:127]
	v_add_u32_e32 v209, s25, v233
	ds_read_b128 v[184:187], v209
	v_exp_f32_e32 v210, v134
	v_exp_f32_e32 v211, v135
	v_mfma_f32_16x16x32_bf16 v[132:135], v[176:179], v[0:3], v[148:151]
	v_mfma_f32_16x16x32_bf16 v[160:163], v[176:179], v[36:39], v[160:163]
	s_nop 1
	v_add_f32_e32 v148, v153, v206
	v_add_f32_e32 v149, v137, v207
	ds_read_b128 v[176:179], v209 offset:4096
	v_mfma_f32_16x16x32_bf16 v[164:167], v[180:183], v[0:3], v[164:167]
	v_exp_f32_e32 v212, v128
	v_exp_f32_e32 v213, v129
	v_add_f32_e32 v148, v154, v148
	v_mfma_f32_16x16x32_bf16 v[168:171], v[180:183], v[36:39], v[168:171]
	v_add_f32_e32 v149, v138, v149
	ds_read_b128 v[180:183], v209 offset:8192
	v_exp_f32_e32 v219, v130
	v_exp_f32_e32 v235, v131
	v_mfma_f32_16x16x32_bf16 v[128:131], v[236:239], v[0:3], v[140:143]
	v_add_f32_e32 v148, v155, v148
	v_add_f32_e32 v149, v139, v149
	v_mfma_f32_16x16x32_bf16 v[140:143], v[236:239], v[36:39], v[172:175]
	s_nop 2
	ds_read_b128 v[172:175], v209 offset:12288
	s_waitcnt lgkmcnt(0)
	v_mfma_f32_16x16x32_bf16 v[120:123], v[184:187], v[28:31], v[120:123]
	v_add_f32_e32 v150, v188, v148
	v_add_f32_e32 v149, v190, v149
	v_mfma_f32_16x16x32_bf16 v[124:127], v[184:187], v[12:15], v[124:127]
	v_cvt_pk_bf16_f32 v148, v156, v157
	v_add_u32_e32 v206, s25, v230
	ds_read_b128 v[184:187], v206
	v_add_f32_e32 v150, v189, v150
	v_add_f32_e32 v151, v191, v149
	v_mfma_f32_16x16x32_bf16 v[132:135], v[176:179], v[12:15], v[132:135]
	v_cvt_pk_bf16_f32 v149, v158, v159
	v_mfma_f32_16x16x32_bf16 v[156:159], v[176:179], v[28:31], v[160:163]
	ds_read_b128 v[176:179], v206 offset:4096
	v_mfma_f32_16x16x32_bf16 v[162:165], v[180:183], v[12:15], v[164:167]
	s_nop 0
	v_add_f32_e32 v160, v194, v150
	v_add_f32_e32 v151, v192, v151
	v_mfma_f32_16x16x32_bf16 v[166:169], v[180:183], v[28:31], v[168:171]
	v_cvt_pk_bf16_f32 v150, v152, v153
	ds_read_b128 v[180:183], v206 offset:8192
	v_mfma_f32_16x16x32_bf16 v[128:131], v[172:175], v[12:15], v[128:131]
	v_add_f32_e32 v160, v195, v160
	v_add_f32_e32 v161, v193, v151
	v_mfma_f32_16x16x32_bf16 v[140:143], v[172:175], v[28:31], v[140:143]
	v_cvt_pk_bf16_f32 v151, v154, v155
	ds_read_b128 v[152:155], v206 offset:12288
	s_waitcnt lgkmcnt(0)
	v_mfma_f32_16x16x32_bf16 v[120:123], v[184:187], v[24:27], v[120:123]
	v_add_f32_e32 v174, v196, v160
	v_add_f32_e32 v161, v212, v161
	v_mfma_f32_16x16x32_bf16 v[124:127], v[184:187], v[8:11], v[124:127]
	v_cvt_pk_bf16_f32 v160, v144, v145
	v_add_u32_e32 v186, s25, v226
	ds_read_b128 v[170:173], v186 offset:16384
	v_add_f32_e32 v184, v208, v174
	v_add_f32_e32 v185, v213, v161
	v_mfma_f32_16x16x32_bf16 v[132:135], v[176:179], v[8:11], v[132:135]
	v_cvt_pk_bf16_f32 v161, v146, v147
	v_mfma_f32_16x16x32_bf16 v[144:147], v[176:179], v[24:27], v[156:159]
	s_nop 2
	ds_read_b128 v[156:159], v186 offset:18432
	v_mfma_f32_16x16x32_bf16 v[174:177], v[180:183], v[8:11], v[162:165]
	v_mfma_f32_16x16x32_bf16 v[178:181], v[180:183], v[24:27], v[166:169]
	s_nop 1
	v_add_f32_e32 v163, v210, v184
	v_add_f32_e32 v164, v219, v185
	v_cvt_pk_bf16_f32 v162, v136, v137
	ds_read_b128 v[182:185], v186 offset:20480
	v_add_f32_e32 v206, v211, v163
	v_add_f32_e32 v207, v235, v164
	v_mfma_f32_16x16x32_bf16 v[128:131], v[152:155], v[8:11], v[128:131]
	v_cvt_pk_bf16_f32 v163, v138, v139
	v_mfma_f32_16x16x32_bf16 v[136:139], v[152:155], v[24:27], v[140:143]
	s_nop 2
	ds_read_b128 v[140:143], v186 offset:22528
	s_waitcnt lgkmcnt(0)
	v_mfma_f32_16x16x32_bf16 v[120:123], v[170:173], v[32:35], v[120:123]
	v_cvt_pk_bf16_f32 v164, v188, v189
	v_mfma_f32_16x16x32_bf16 v[124:127], v[170:173], v[16:19], v[124:127]
	v_add_u32_e32 v152, s25, v224
	ds_read_b128 v[168:171], v152 offset:16384
	v_mfma_f32_16x16x32_bf16 v[132:135], v[156:159], v[16:19], v[132:135]
	v_cvt_pk_bf16_f32 v165, v194, v195
	v_mfma_f32_16x16x32_bf16 v[186:189], v[156:159], v[32:35], v[144:147]
	ds_read_b128 v[236:239], v152 offset:18432
	v_mfma_f32_16x16x32_bf16 v[240:243], v[182:185], v[16:19], v[174:177]
	v_cvt_pk_bf16_f32 v166, v196, v208
	v_mfma_f32_16x16x32_bf16 v[176:179], v[182:185], v[32:35], v[178:181]
	s_nop 2
	ds_read_b128 v[180:183], v152 offset:20480
	v_mfma_f32_16x16x32_bf16 v[128:131], v[140:143], v[16:19], v[128:131]
	v_cvt_pk_bf16_f32 v167, v210, v211
	v_mfma_f32_16x16x32_bf16 v[244:247], v[140:143], v[32:35], v[136:139]
	ds_read_b128 v[248:251], v152 offset:22528
	s_waitcnt lgkmcnt(0)
	v_mfma_f32_16x16x32_bf16 v[152:155], v[168:171], v[20:23], v[124:127]
	v_mfma_f32_16x16x32_bf16 v[144:147], v[168:171], v[44:47], v[120:123]
	v_cvt_pk_bf16_f32 v168, v190, v191
	v_mfma_f32_16x16x32_bf16 v[156:159], v[236:239], v[20:23], v[132:135]
	v_cvt_pk_bf16_f32 v169, v192, v193
	v_mfma_f32_16x16x32_bf16 v[172:175], v[236:239], v[44:47], v[186:189]
	v_mfma_f32_16x16x32_bf16 v[140:143], v[180:183], v[20:23], v[240:243]
	v_cvt_pk_bf16_f32 v170, v212, v213
	v_mfma_f32_16x16x32_bf16 v[136:139], v[180:183], v[44:47], v[176:179]
	v_mfma_f32_16x16x32_bf16 v[132:135], v[248:251], v[20:23], v[128:131]
	v_cvt_pk_bf16_f32 v171, v219, v235
	v_mfma_f32_16x16x32_bf16 v[128:131], v[248:251], v[44:47], v[244:247]
	s_lshl_b32 s34, s8, 14
	s_add_i32 s48, s34, 0
	s_add_i32 s48, s48, 0x12000
	v_add_u32_e32 v196, s48, v222
	v_add_u32_e32 v219, s48, v223
	ds_read_b64_tr_b16 v[120:121], v196
	ds_read_b64_tr_b16 v[122:123], v196 offset:4096
	ds_read_b64_tr_b16 v[124:125], v196 offset:8192
	ds_read_b64_tr_b16 v[126:127], v196 offset:12288
	ds_read_b64_tr_b16 v[176:177], v219
	ds_read_b64_tr_b16 v[178:179], v219 offset:4096
	ds_read_b64_tr_b16 v[182:183], v219 offset:4608
	ds_read_b64_tr_b16 v[180:181], v219 offset:512
	ds_read_b64_tr_b16 v[184:185], v219 offset:8192
	ds_read_b64_tr_b16 v[186:187], v219 offset:12288
	ds_read_b64_tr_b16 v[190:191], v219 offset:12800
	ds_read_b64_tr_b16 v[188:189], v219 offset:8704
	s_waitcnt lgkmcnt(0)
	v_mfma_f32_16x16x32_bf16 v[112:115], v[176:179], v[148:151], v[112:115]
	v_mfma_f32_16x16x32_bf16 v[116:119], v[176:179], v[160:163], v[116:119]
	v_max_f32_e32 v176, v152, v153
	v_mfma_f32_16x16x32_bf16 v[112:115], v[184:187], v[164:167], v[112:115]
	v_max3_f32 v176, v176, v154, v155
	v_max3_f32 v176, v176, v156, v157
	v_max3_f32 v208, v176, v158, v159
	v_mfma_f32_16x16x32_bf16 v[116:119], v[184:187], v[168:171], v[116:119]
	ds_read_b64_tr_b16 v[192:193], v196 offset:512
	ds_read_b64_tr_b16 v[194:195], v196 offset:4608
	ds_read_b64_tr_b16 v[236:237], v196 offset:8704
	ds_read_b64_tr_b16 v[238:239], v196 offset:12800
	v_mfma_f32_16x16x32_bf16 v[108:111], v[120:123], v[148:151], v[108:111]
	v_mfma_f32_16x16x32_bf16 v[176:179], v[120:123], v[160:163], v[104:107]
	v_mfma_f32_16x16x32_bf16 v[104:107], v[124:127], v[164:167], v[108:111]
	s_nop 5
	v_max3_f32 v108, v208, v140, v141
	v_max3_f32 v108, v108, v142, v143
	v_max3_f32 v108, v108, v132, v133
	v_max3_f32 v120, v108, v134, v135
	v_mfma_f32_16x16x32_bf16 v[108:111], v[124:127], v[168:171], v[176:179]
	ds_read_b64_tr_b16 v[184:185], v219 offset:1024
	ds_read_b64_tr_b16 v[186:187], v219 offset:5120
	s_nop 0
	ds_read_b64_tr_b16 v[176:177], v219 offset:9216
	ds_read_b64_tr_b16 v[178:179], v219 offset:13312
	v_mfma_f32_16x16x32_bf16 v[96:99], v[180:183], v[148:151], v[96:99]
	v_max_f32_e32 v121, v144, v145
	v_mfma_f32_16x16x32_bf16 v[96:99], v[188:191], v[164:167], v[96:99]
	v_max3_f32 v121, v121, v146, v147
	v_max3_f32 v121, v121, v172, v173
	v_max3_f32 v121, v121, v174, v175
	v_mfma_f32_16x16x32_bf16 v[100:103], v[180:183], v[160:163], v[100:103]
	v_mfma_f32_16x16x32_bf16 v[100:103], v[188:191], v[168:171], v[100:103]
	ds_read_b64_tr_b16 v[188:189], v196 offset:1024
	ds_read_b64_tr_b16 v[190:191], v196 offset:5120
	ds_read_b64_tr_b16 v[180:181], v196 offset:9216
	ds_read_b64_tr_b16 v[182:183], v196 offset:13312
	s_waitcnt lgkmcnt(0)
	v_mfma_f32_16x16x32_bf16 v[92:95], v[192:195], v[148:151], v[92:95]
	v_mfma_f32_16x16x32_bf16 v[122:125], v[192:195], v[160:163], v[88:91]
	v_mfma_f32_16x16x32_bf16 v[88:91], v[236:239], v[164:167], v[92:95]
	s_nop 5
	v_max3_f32 v92, v121, v136, v137
	v_max3_f32 v92, v92, v138, v139
	v_max3_f32 v92, v92, v128, v129
	v_max3_f32 v121, v92, v130, v131
	v_mfma_f32_16x16x32_bf16 v[92:95], v[236:239], v[168:171], v[122:125]
	s_nop 2
	v_max_f32_e32 v122, v120, v121
	v_cmp_ge_f32_e32 vcc, s62, v122
	s_cmp_lg_u64 vcc, exec
	s_cselect_b64 s[34:35], -1, 0
	s_cmp_eq_u64 vcc, exec
	s_cbranch_scc1 .LBB0_965
	ds_bpermute_b32 v48, v220, v120
	v_max_f32_e32 v49, v120, v120
	v_max_f32_e32 v50, v121, v121
	s_waitcnt lgkmcnt(0)
	v_max_f32_e32 v48, v48, v48
	v_max_f32_e32 v48, v49, v48
	ds_bpermute_b32 v49, v221, v48
	s_waitcnt lgkmcnt(0)
	v_max3_f32 v48, v48, v49, 0
	ds_bpermute_b32 v49, v220, v121
	v_exp_f32_e64 v208, -v48
	v_sub_f32_e32 v152, v152, v48
	v_sub_f32_e32 v153, v153, v48
	v_sub_f32_e32 v154, v154, v48
	s_waitcnt lgkmcnt(0)
	v_max_f32_e32 v49, v49, v49
	v_max_f32_e32 v49, v50, v49
	ds_bpermute_b32 v50, v221, v49
	v_sub_f32_e32 v155, v155, v48
	v_sub_f32_e32 v156, v156, v48
	v_sub_f32_e32 v157, v157, v48
	v_sub_f32_e32 v158, v158, v48
	s_waitcnt lgkmcnt(0)
	v_max3_f32 v49, v49, v50, 0
	v_exp_f32_e64 v209, -v49
	v_pk_add_f32 v[202:203], v[202:203], v[48:49]
	v_sub_f32_e32 v159, v159, v48
	v_pk_add_f32 v[120:121], v[202:203], 0 neg_lo:[1,1] neg_hi:[1,1]
	v_xor_b32_e32 v124, 0x80000000, v203
	v_sub_f32_e32 v143, v143, v48
	v_sub_f32_e32 v142, v142, v48
	v_sub_f32_e32 v141, v141, v48
	v_sub_f32_e32 v140, v140, v48
	v_sub_f32_e32 v135, v135, v48
	v_sub_f32_e32 v134, v134, v48
	v_sub_f32_e32 v133, v133, v48
	v_sub_f32_e32 v132, v132, v48
	v_mov_b32_e32 v121, v120
	v_mov_b32_e32 v122, v120
	v_mov_b32_e32 v123, v120
	v_sub_f32_e32 v144, v144, v49
	v_sub_f32_e32 v145, v145, v49
	v_sub_f32_e32 v146, v146, v49
	v_sub_f32_e32 v147, v147, v49
	v_sub_f32_e32 v172, v172, v49
	v_sub_f32_e32 v173, v173, v49
	v_sub_f32_e32 v174, v174, v49
	v_sub_f32_e32 v175, v175, v49
	v_sub_f32_e32 v139, v139, v49
	v_sub_f32_e32 v138, v138, v49
	v_sub_f32_e32 v137, v137, v49
	v_sub_f32_e32 v136, v136, v49
	v_sub_f32_e32 v131, v131, v49
	v_sub_f32_e32 v130, v130, v49
	v_sub_f32_e32 v129, v129, v49
	v_sub_f32_e32 v128, v128, v49
	v_mov_b32_e32 v125, v124
	v_mov_b32_e32 v126, v124
	v_mov_b32_e32 v127, v124
	v_mov_b32_e32 v48, v120
	v_mov_b32_e32 v49, v120
	v_mov_b32_e32 v50, v120
	v_mov_b32_e32 v51, v120
	v_mov_b32_e32 v52, v124
	v_mov_b32_e32 v53, v124
	v_mov_b32_e32 v54, v124
	v_mov_b32_e32 v55, v124
	s_branch .LBB0_966

.LBB0_969:
	s_waitcnt vmcnt(5)
	s_barrier
	s_mul_i32 s34, s19, 0x6000
	s_add_i32 s49, s34, 0
	v_add_u32_e32 v164, s49, v225
	ds_read_b128 v[160:163], v164
	ds_read_b128 v[168:171], v164 offset:4096
	ds_read_b128 v[184:187], v164 offset:8192
	ds_read_b128 v[246:249], v164 offset:12288
	s_waitcnt lgkmcnt(0)
	v_mfma_f32_16x16x32_bf16 v[164:167], v[160:163], v[4:7], v[120:123]
	v_exp_f32_e32 v235, v140
	v_exp_f32_e32 v236, v141
	v_mfma_f32_16x16x32_bf16 v[160:163], v[160:163], v[40:43], v[124:127]
	v_add_u32_e32 v243, s49, v234
	ds_read_b128 v[192:195], v243
	v_mfma_f32_16x16x32_bf16 v[180:183], v[168:171], v[4:7], v[120:123]
	v_exp_f32_e32 v241, v142
	v_exp_f32_e32 v242, v143
	v_add_f32_e32 v140, v153, v152
	v_mfma_f32_16x16x32_bf16 v[172:175], v[168:171], v[40:43], v[124:127]
	v_add_f32_e32 v141, v145, v144
	ds_read_b128 v[188:191], v243 offset:4096
	v_exp_f32_e32 v237, v136
	v_exp_f32_e32 v238, v137
	v_mfma_f32_16x16x32_bf16 v[176:179], v[184:187], v[4:7], v[120:123]
	v_add_f32_e32 v136, v154, v140
	v_add_f32_e32 v137, v146, v141
	v_mfma_f32_16x16x32_bf16 v[140:143], v[184:187], v[40:43], v[124:127]
	ds_read_b128 v[184:187], v243 offset:8192
	v_exp_f32_e32 v239, v138
	v_exp_f32_e32 v240, v139
	v_mfma_f32_16x16x32_bf16 v[168:171], v[246:249], v[4:7], v[120:123]
	v_add_f32_e32 v245, v155, v136
	v_add_f32_e32 v244, v147, v137
	v_mfma_f32_16x16x32_bf16 v[136:139], v[246:249], v[40:43], v[124:127]
	s_cmp_ge_u32 s4, s2
	s_cselect_b64 s[34:35], -1, 0
	s_and_b64 vcc, exec, s[34:35]
	s_cbranch_vccnz .LBB0_971
	s_add_u32 s65, s6, s30
	s_addc_u32 s69, s7, s31
	s_add_u32 s70, s65, 0x200000
	s_addc_u32 s71, s69, 0
	s_add_i32 s65, s25, s77
	s_mov_b64 s[80:81], s[10:11]
	s_mov_b32 m0, s65
	s_add_i32 s25, s25, s97
	global_load_lds_dwordx4 v227, s[70:71]
	s_add_i32 m0, s65, 0x400
	s_nop 0
	global_load_lds_dwordx4 v229, s[70:71]
	s_add_i32 m0, s25, 0x4000
	s_nop 0
	global_load_lds_dwordx4 v232, s[80:81]
.LBB0_971:
	s_add_u32 s36, s36, 0x180000
	s_addc_u32 s37, s37, 0
	s_add_i32 s25, s48, s77
	s_mov_b32 m0, s25
	s_nop 0
	global_load_lds_dwordx4 v228, s[36:37]
	s_add_i32 m0, s25, 0x400
	s_nop 0
	global_load_lds_dwordx4 v231, s[36:37]
	ds_read_b128 v[246:249], v243 offset:12288
	s_waitcnt lgkmcnt(0)
	v_mfma_f32_16x16x32_bf16 v[164:167], v[192:195], v[0:3], v[164:167]
	v_exp_f32_e32 v210, v132
	v_exp_f32_e32 v211, v133
	v_add_f32_e32 v212, v156, v245
	v_mfma_f32_16x16x32_bf16 v[160:163], v[192:195], v[36:39], v[160:163]
	v_add_f32_e32 v213, v148, v244
	v_add_u32_e32 v243, s49, v233
	ds_read_b128 v[192:195], v243
	v_exp_f32_e32 v250, v134
	v_exp_f32_e32 v251, v135
	v_mfma_f32_16x16x32_bf16 v[132:135], v[188:191], v[0:3], v[180:183]
	v_add_f32_e32 v212, v157, v212
	v_add_f32_e32 v213, v149, v213
	v_mfma_f32_16x16x32_bf16 v[172:175], v[188:191], v[36:39], v[172:175]
	ds_read_b128 v[180:183], v243 offset:4096
	v_mfma_f32_16x16x32_bf16 v[176:179], v[184:187], v[0:3], v[176:179]
	v_exp_f32_e32 v215, v128
	v_exp_f32_e32 v214, v129
	v_add_f32_e32 v188, v158, v212
	v_mfma_f32_16x16x32_bf16 v[140:143], v[184:187], v[36:39], v[140:143]
	v_add_f32_e32 v189, v150, v213
	ds_read_b128 v[184:187], v243 offset:8192
	v_exp_f32_e32 v218, v130
	v_exp_f32_e32 v198, v131
	v_mfma_f32_16x16x32_bf16 v[128:131], v[246:249], v[0:3], v[168:171]
	v_add_f32_e32 v199, v159, v188
	v_add_f32_e32 v212, v151, v189
	v_mfma_f32_16x16x32_bf16 v[168:171], v[246:249], v[36:39], v[136:139]
	ds_read_b128 v[188:191], v243 offset:12288
	s_waitcnt lgkmcnt(0)
	v_mfma_f32_16x16x32_bf16 v[164:167], v[192:195], v[12:15], v[164:167]
	v_add_f32_e32 v137, v235, v199
	v_add_f32_e32 v138, v237, v212
	v_mfma_f32_16x16x32_bf16 v[160:163], v[192:195], v[28:31], v[160:163]
	v_cvt_pk_bf16_f32 v136, v152, v153
	v_add_u32_e32 v199, s49, v230
	ds_read_b128 v[192:195], v199
	v_add_f32_e32 v139, v236, v137
	v_add_f32_e32 v138, v238, v138
	v_mfma_f32_16x16x32_bf16 v[132:135], v[180:183], v[12:15], v[132:135]
	v_cvt_pk_bf16_f32 v137, v154, v155
	v_mfma_f32_16x16x32_bf16 v[152:155], v[180:183], v[28:31], v[172:175]
	s_nop 2
	ds_read_b128 v[172:175], v199 offset:4096
	v_mfma_f32_16x16x32_bf16 v[176:179], v[184:187], v[12:15], v[176:179]
	v_add_f32_e32 v139, v241, v139
	v_add_f32_e32 v212, v239, v138
	v_mfma_f32_16x16x32_bf16 v[140:143], v[184:187], v[28:31], v[140:143]
	v_cvt_pk_bf16_f32 v138, v156, v157
	ds_read_b128 v[180:183], v199 offset:8192
	v_add_f32_e32 v213, v242, v139
	v_add_f32_e32 v212, v240, v212
	v_mfma_f32_16x16x32_bf16 v[128:131], v[188:191], v[12:15], v[128:131]
	v_cvt_pk_bf16_f32 v139, v158, v159
	v_mfma_f32_16x16x32_bf16 v[156:159], v[188:191], v[28:31], v[168:171]
	s_nop 2
	ds_read_b128 v[168:171], v199 offset:12288
	s_waitcnt lgkmcnt(0)
	v_mfma_f32_16x16x32_bf16 v[164:167], v[192:195], v[8:11], v[164:167]
	v_mfma_f32_16x16x32_bf16 v[184:187], v[192:195], v[24:27], v[160:163]
	s_nop 2
	v_add_f32_e32 v161, v210, v213
	v_add_f32_e32 v162, v215, v212
	v_cvt_pk_bf16_f32 v160, v144, v145
	v_add_u32_e32 v192, s49, v226
	ds_read_b128 v[188:191], v192 offset:16384
	v_add_f32_e32 v163, v211, v161
	v_add_f32_e32 v162, v214, v162
	v_mfma_f32_16x16x32_bf16 v[132:135], v[172:175], v[8:11], v[132:135]
	v_cvt_pk_bf16_f32 v161, v146, v147
	v_mfma_f32_16x16x32_bf16 v[144:147], v[172:175], v[24:27], v[152:155]
	s_nop 2
	ds_read_b128 v[152:155], v192 offset:18432
	v_mfma_f32_16x16x32_bf16 v[172:175], v[180:183], v[8:11], v[176:179]
	v_add_f32_e32 v163, v250, v163
	v_add_f32_e32 v193, v218, v162
	v_mfma_f32_16x16x32_bf16 v[140:143], v[180:183], v[24:27], v[140:143]
	v_cvt_pk_bf16_f32 v162, v148, v149
	ds_read_b128 v[176:179], v192 offset:20480
	v_add_f32_e32 v194, v251, v163
	v_add_f32_e32 v195, v198, v193
	v_mfma_f32_16x16x32_bf16 v[128:131], v[168:171], v[8:11], v[128:131]
	v_cvt_pk_bf16_f32 v163, v150, v151
	v_mfma_f32_16x16x32_bf16 v[148:151], v[168:171], v[24:27], v[156:159]
	s_nop 2
	ds_read_b128 v[156:159], v192 offset:22528
	s_waitcnt lgkmcnt(0)
	v_mfma_f32_16x16x32_bf16 v[168:171], v[188:191], v[16:19], v[164:167]
	v_cvt_pk_bf16_f32 v164, v235, v236
	v_mfma_f32_16x16x32_bf16 v[180:183], v[188:191], v[32:35], v[184:187]
	v_add_u32_e32 v192, s49, v224
	s_nop 1
	ds_read_b128 v[184:187], v192 offset:16384
	v_mfma_f32_16x16x32_bf16 v[132:135], v[152:155], v[16:19], v[132:135]
	v_cvt_pk_bf16_f32 v165, v241, v242
	v_mfma_f32_16x16x32_bf16 v[188:191], v[152:155], v[32:35], v[144:147]
	ds_read_b128 v[242:245], v192 offset:18432
	v_mfma_f32_16x16x32_bf16 v[140:143], v[176:179], v[32:35], v[140:143]
	v_cvt_pk_bf16_f32 v166, v210, v211
	v_mfma_f32_16x16x32_bf16 v[246:249], v[176:179], v[16:19], v[172:175]
	ds_read_b128 v[176:179], v192 offset:20480
	v_mfma_f32_16x16x32_bf16 v[128:131], v[156:159], v[16:19], v[128:131]
	v_cvt_pk_bf16_f32 v167, v250, v251
	v_mfma_f32_16x16x32_bf16 v[250:253], v[156:159], v[32:35], v[148:151]
	ds_read_b128 v[210:213], v192 offset:22528
	s_waitcnt lgkmcnt(0)
	v_mfma_f32_16x16x32_bf16 v[156:159], v[184:187], v[20:23], v[168:171]
	v_cvt_pk_bf16_f32 v168, v237, v238
	v_mfma_f32_16x16x32_bf16 v[144:147], v[184:187], v[44:47], v[180:183]
	v_mfma_f32_16x16x32_bf16 v[152:155], v[242:245], v[20:23], v[132:135]
	v_cvt_pk_bf16_f32 v169, v239, v240
	v_mfma_f32_16x16x32_bf16 v[172:175], v[242:245], v[44:47], v[188:191]
	v_mfma_f32_16x16x32_bf16 v[148:151], v[176:179], v[20:23], v[246:249]
	v_cvt_pk_bf16_f32 v170, v215, v214
	v_mfma_f32_16x16x32_bf16 v[140:143], v[176:179], v[44:47], v[140:143]
	v_mfma_f32_16x16x32_bf16 v[132:135], v[210:213], v[20:23], v[128:131]
	v_cvt_pk_bf16_f32 v171, v218, v198
	v_mfma_f32_16x16x32_bf16 v[128:131], v[210:213], v[44:47], v[250:253]
	s_lshl_b32 s25, s5, 14
	s_add_i32 s25, s25, 0
	s_add_i32 s25, s25, 0x12000
	v_add_u32_e32 v235, s25, v222
	v_add_u32_e32 v236, s25, v223
	ds_read_b64_tr_b16 v[176:177], v235
	ds_read_b64_tr_b16 v[178:179], v235 offset:4096
	ds_read_b64_tr_b16 v[180:181], v235 offset:8192
	ds_read_b64_tr_b16 v[182:183], v235 offset:12288
	ds_read_b64_tr_b16 v[184:185], v236
	ds_read_b64_tr_b16 v[186:187], v236 offset:4096
	ds_read_b64_tr_b16 v[190:191], v236 offset:4608
	ds_read_b64_tr_b16 v[188:189], v236 offset:512
	ds_read_b64_tr_b16 v[210:211], v236 offset:8192
	ds_read_b64_tr_b16 v[212:213], v236 offset:12288
	ds_read_b64_tr_b16 v[240:241], v236 offset:12800
	ds_read_b64_tr_b16 v[238:239], v236 offset:8704
	s_waitcnt lgkmcnt(0)
	v_mfma_f32_16x16x32_bf16 v[112:115], v[184:187], v[136:139], v[112:115]
	v_mfma_f32_16x16x32_bf16 v[116:119], v[184:187], v[160:163], v[116:119]
	v_max_f32_e32 v184, v156, v157
	v_mfma_f32_16x16x32_bf16 v[112:115], v[210:213], v[164:167], v[112:115]
	v_max3_f32 v184, v184, v158, v159
	v_max3_f32 v184, v184, v152, v153
	v_max3_f32 v184, v184, v154, v155
	v_mfma_f32_16x16x32_bf16 v[116:119], v[210:213], v[168:171], v[116:119]
	ds_read_b64_tr_b16 v[210:211], v235 offset:512
	ds_read_b64_tr_b16 v[212:213], v235 offset:4608
	ds_read_b64_tr_b16 v[242:243], v235 offset:8704
	ds_read_b64_tr_b16 v[244:245], v235 offset:12800
	v_mfma_f32_16x16x32_bf16 v[104:107], v[176:179], v[136:139], v[104:107]
	v_mfma_f32_16x16x32_bf16 v[176:179], v[176:179], v[160:163], v[108:111]
	v_mfma_f32_16x16x32_bf16 v[108:111], v[180:183], v[164:167], v[104:107]
	s_nop 5
	v_max3_f32 v104, v184, v148, v149
	v_max3_f32 v104, v104, v150, v151
	v_max3_f32 v104, v104, v132, v133
	v_max3_f32 v193, v104, v134, v135
	v_mfma_f32_16x16x32_bf16 v[104:107], v[180:183], v[168:171], v[176:179]
	ds_read_b64_tr_b16 v[184:185], v236 offset:1024
	ds_read_b64_tr_b16 v[186:187], v236 offset:5120
	s_nop 0
	ds_read_b64_tr_b16 v[176:177], v236 offset:9216
	ds_read_b64_tr_b16 v[178:179], v236 offset:13312
	v_mfma_f32_16x16x32_bf16 v[96:99], v[188:191], v[136:139], v[96:99]
	v_max_f32_e32 v180, v144, v145
	v_mfma_f32_16x16x32_bf16 v[96:99], v[238:241], v[164:167], v[96:99]
	v_max3_f32 v180, v180, v146, v147
	v_max3_f32 v180, v180, v172, v173
	v_max3_f32 v192, v180, v174, v175
	v_mfma_f32_16x16x32_bf16 v[100:103], v[188:191], v[160:163], v[100:103]
	v_mfma_f32_16x16x32_bf16 v[100:103], v[238:241], v[168:171], v[100:103]
	ds_read_b64_tr_b16 v[188:189], v235 offset:1024
	ds_read_b64_tr_b16 v[190:191], v235 offset:5120
	ds_read_b64_tr_b16 v[180:181], v235 offset:9216
	ds_read_b64_tr_b16 v[182:183], v235 offset:13312
	s_waitcnt lgkmcnt(0)
	v_mfma_f32_16x16x32_bf16 v[88:91], v[210:213], v[136:139], v[88:91]
	v_mfma_f32_16x16x32_bf16 v[210:213], v[210:213], v[160:163], v[92:95]
	v_mfma_f32_16x16x32_bf16 v[92:95], v[242:245], v[164:167], v[88:91]
	s_nop 5
	v_max3_f32 v88, v192, v140, v141
	v_max3_f32 v88, v88, v142, v143
	v_max3_f32 v88, v88, v128, v129
	v_max3_f32 v237, v88, v130, v131
	v_mfma_f32_16x16x32_bf16 v[88:91], v[242:245], v[168:171], v[210:213]
	v_max_f32_e32 v192, v193, v237
	v_cmp_ge_f32_e32 vcc, s62, v192
	s_cmp_lg_u64 vcc, exec
	s_cselect_b64 s[36:37], -1, 0
	s_cmp_eq_u64 vcc, exec
	v_mov_b32_e32 v192, 1.0
	s_cbranch_scc1 .LBB0_973
	ds_bpermute_b32 v48, v220, v193
	v_max_f32_e32 v49, v193, v193
	v_max_f32_e32 v50, v237, v237
	s_waitcnt lgkmcnt(0)
	v_max_f32_e32 v48, v48, v48
	v_max_f32_e32 v48, v49, v48
	ds_bpermute_b32 v49, v221, v48
	s_waitcnt lgkmcnt(0)
	v_max3_f32 v48, v48, v49, 0
	ds_bpermute_b32 v49, v220, v237
	v_exp_f32_e64 v192, -v48
	v_sub_f32_e32 v156, v156, v48
	v_sub_f32_e32 v157, v157, v48
	v_sub_f32_e32 v158, v158, v48
	s_waitcnt lgkmcnt(0)
	v_max_f32_e32 v49, v49, v49
	v_max_f32_e32 v49, v50, v49
	ds_bpermute_b32 v50, v221, v49
	v_sub_f32_e32 v159, v159, v48
	v_sub_f32_e32 v152, v152, v48
	v_sub_f32_e32 v153, v153, v48
	v_sub_f32_e32 v154, v154, v48
	s_waitcnt lgkmcnt(0)
	v_max3_f32 v49, v49, v50, 0
	v_exp_f32_e64 v193, -v49
	v_pk_add_f32 v[202:203], v[202:203], v[48:49]
	v_sub_f32_e32 v155, v155, v48
	v_pk_add_f32 v[120:121], v[202:203], 0 neg_lo:[1,1] neg_hi:[1,1]
	v_xor_b32_e32 v124, 0x80000000, v203
	v_sub_f32_e32 v151, v151, v48
	v_sub_f32_e32 v150, v150, v48
	v_sub_f32_e32 v149, v149, v48
	v_sub_f32_e32 v148, v148, v48
	v_sub_f32_e32 v135, v135, v48
	v_sub_f32_e32 v134, v134, v48
	v_sub_f32_e32 v133, v133, v48
	v_sub_f32_e32 v132, v132, v48
	v_mov_b32_e32 v121, v120
	v_mov_b32_e32 v122, v120
	v_mov_b32_e32 v123, v120
	v_sub_f32_e32 v144, v144, v49
	v_sub_f32_e32 v145, v145, v49
	v_sub_f32_e32 v146, v146, v49
	v_sub_f32_e32 v147, v147, v49
	v_sub_f32_e32 v172, v172, v49
	v_sub_f32_e32 v173, v173, v49
	v_sub_f32_e32 v174, v174, v49
	v_sub_f32_e32 v175, v175, v49
	v_sub_f32_e32 v143, v143, v49
	v_sub_f32_e32 v142, v142, v49
	v_sub_f32_e32 v141, v141, v49
	v_sub_f32_e32 v140, v140, v49
	v_sub_f32_e32 v131, v131, v49
	v_sub_f32_e32 v130, v130, v49
	v_sub_f32_e32 v129, v129, v49
	v_sub_f32_e32 v128, v128, v49
	v_mov_b32_e32 v125, v124
	v_mov_b32_e32 v126, v124
	v_mov_b32_e32 v127, v124
	v_mov_b32_e32 v48, v120
	v_mov_b32_e32 v49, v120
	v_mov_b32_e32 v50, v120
	v_mov_b32_e32 v51, v120
	v_mov_b32_e32 v52, v124
	v_mov_b32_e32 v53, v124
	v_mov_b32_e32 v54, v124
	v_mov_b32_e32 v55, v124
	s_branch .LBB0_974
